# v32 + in-proj K-loop: removed the four back-to-back s_setprio 0/1 pairs between MFMA groups
# baseline (speedup 1.0000x reference)
; #define PG8_STAGE(bufoff, gbase, voff) do { _Pragma("unroll") for (int _i = 0; _i < 2; ++_i) \
;         __builtin_amdgcn_global_load_lds((const unsigned*)((const char*)(gbase) + (voff)[_i]), (LAS unsigned*)(lds + (bufoff) + ldsw + _i * 8192), 16, 0, 0); } while (0)
; #define PG8_LDA(dst, b, h) do { _Pragma("unroll") for (int m = 0; m < 4; ++m) _Pragma("unroll") for (int k = 0; k < 2; ++k) dst[m][k] = *(const LAS bf16x8*)(lds + PG8_SA(b, h) + aoff + m * 2048 + k * 1024); } while (0)
; #define PG8_LDB(dst, b, h) do { _Pragma("unroll") for (int n = 0; n < 2; ++n) _Pragma("unroll") for (int k = 0; k < 2; ++k) dst[n][k] = *(const LAS bf16x8*)(lds + PG8_SB(b, h) + boff + n * 2048 + k * 1024); } while (0)
; template <class Epi, class Sched, bool HALFN = false>
; __device__ __forceinline__ void gemm_phase(LAS unsigned char* lds, const Gemm g, const Sched& S, const Epi& E, int wave_s) {
;     ...
;         for (int t = 0; t < nt; t += 2) {
;             const bool last = (t == nt - 2);
;             const char* a1 = cA + (size_t)(t + 1) * kstep;
;             const char* a2 = last ? nA : cA + (size_t)(t + 2) * kstep; const char* b2 = last ? nB : cB + (size_t)(t + 2) * kstep;
;             const char* a3 = a2 + kstep; const char* b3 = b2 + kstep;
;             PG8_LDB(B0, 0, 0); if (!HALFN) PG8_LDB(B1, 0, 1); PG8_SCHED; PG8_LDA(At, 0, 0); PG8_STAGE(PG8_SA(1, 1), a1 + hstep, voffA);
;             PG8_WAIT_V(8); PG8_WAIT_L(0); PG8_BAR; PG8_MMA(0, 0, At, B0); if (!HALFN) PG8_MMA(0, 1, At, B1); PG8_BAR; PG8_SCHED;
;             PG8_LDA(At, 0, 1); PG8_STAGE(PG8_SB(0, 0), b2, voffB); PG8_STAGE(PG8_SB(0, 1), b2 + bh1, voffB); PG8_STAGE(PG8_SA(0, 0), a2, voffA);
;             PG8_WAIT_V(8); PG8_WAIT_L(0); PG8_BAR; PG8_MMA(1, 0, At, B0); if (!HALFN) PG8_MMA(1, 1, At, B1); PG8_BAR; PG8_SCHED;
;             PG8_LDB(B0, 1, 0); if (!HALFN) PG8_LDB(B1, 1, 1); PG8_SCHED; PG8_LDA(At, 1, 0); PG8_STAGE(PG8_SA(0, 1), a2 + hstep, voffA);
;             PG8_WAIT_V(8); PG8_WAIT_L(0); PG8_BAR; PG8_MMA(0, 0, At, B0); if (!HALFN) PG8_MMA(0, 1, At, B1); PG8_BAR; PG8_SCHED;
;             PG8_LDA(At, 1, 1); PG8_STAGE(PG8_SB(1, 0), b3, voffB); PG8_STAGE(PG8_SB(1, 1), b3 + bh1, voffB); PG8_STAGE(PG8_SA(1, 0), a3, voffA);
;             PG8_WAIT_V(8); PG8_WAIT_L(0); PG8_BAR; PG8_MMA(1, 0, At, B0); if (!HALFN) PG8_MMA(1, 1, At, B1); PG8_BAR; PG8_SCHED;
;         }
;         if (wr == 0) PG8_BAR;
.LBB0_269:
	s_add_u32 s53, s8, 0xfffc0080
	s_addc_u32 s66, s9, -1
	s_add_i32 s82, 0, 0x10000
	s_cmp_eq_u32 s52, 12
	s_cselect_b32 s81, s5, s66
	s_cselect_b32 s80, s7, s53
	v_add_u32_e32 v18, s82, v1
	s_cselect_b32 s79, s39, s48
	s_cselect_b32 s78, s42, s47
	s_add_i32 s53, 0, 0x14000
	ds_read_b128 v[146:149], v18
	ds_read_b128 v[150:153], v18 offset:1024
	ds_read_b128 v[154:157], v18 offset:2048
	ds_read_b128 v[158:161], v18 offset:3072
	v_add_u32_e32 v18, s53, v1
	ds_read_b128 v[162:165], v18
	ds_read_b128 v[166:169], v18 offset:1024
	ds_read_b128 v[172:175], v18 offset:2048
	ds_read_b128 v[176:179], v18 offset:3072
	v_lshl_add_u64 v[196:197], s[8:9], 0, v[140:141]
	s_add_i32 m0, s67, 0xc000
	ds_read_b128 v[180:183], v170
	ds_read_b128 v[184:187], v170 offset:1024
	ds_read_b128 v[188:191], v170 offset:2048
	ds_read_b128 v[192:195], v170 offset:3072
	ds_read_b128 v[208:211], v170 offset:4096
	ds_read_b128 v[212:215], v170 offset:5120
	ds_read_b128 v[216:219], v170 offset:6144
	ds_read_b128 v[220:223], v170 offset:7168
	global_load_lds_dwordx4 v[196:197], off
	v_lshl_add_u64 v[196:197], s[8:9], 0, v[142:143]
	s_add_i32 m0, s67, 0xe000
	s_nop 0
	global_load_lds_dwordx4 v[196:197], off
	s_waitcnt vmcnt(8)
	s_waitcnt lgkmcnt(0)
	s_barrier
	s_setprio 1
	s_waitcnt lgkmcnt(0)
	v_mfma_f32_16x16x32_bf16 v[128:131], v[146:149], v[180:183], v[128:131]
	v_mfma_f32_16x16x32_bf16 v[124:127], v[154:157], v[180:183], v[124:127]
	v_mfma_f32_16x16x32_bf16 v[112:115], v[146:149], v[188:191], v[112:115]
	v_mfma_f32_16x16x32_bf16 v[108:111], v[154:157], v[188:191], v[108:111]
	v_mfma_f32_16x16x32_bf16 v[96:99], v[146:149], v[208:211], v[96:99]
	v_mfma_f32_16x16x32_bf16 v[92:95], v[154:157], v[208:211], v[92:95]
	v_mfma_f32_16x16x32_bf16 v[80:83], v[146:149], v[216:219], v[80:83]
	v_mfma_f32_16x16x32_bf16 v[76:79], v[154:157], v[216:219], v[76:79]
	v_mfma_f32_16x16x32_bf16 v[128:131], v[150:153], v[184:187], v[128:131]
	v_mfma_f32_16x16x32_bf16 v[124:127], v[158:161], v[184:187], v[124:127]
	v_mfma_f32_16x16x32_bf16 v[112:115], v[150:153], v[192:195], v[112:115]
	v_mfma_f32_16x16x32_bf16 v[108:111], v[158:161], v[192:195], v[108:111]
	v_mfma_f32_16x16x32_bf16 v[96:99], v[150:153], v[212:215], v[96:99]
	v_mfma_f32_16x16x32_bf16 v[92:95], v[158:161], v[212:215], v[92:95]
	v_mfma_f32_16x16x32_bf16 v[80:83], v[150:153], v[220:223], v[80:83]
	v_mfma_f32_16x16x32_bf16 v[76:79], v[158:161], v[220:223], v[76:79]
	v_mfma_f32_16x16x32_bf16 v[120:123], v[162:165], v[180:183], v[120:123]
	v_mfma_f32_16x16x32_bf16 v[116:119], v[172:175], v[180:183], v[116:119]
	v_mfma_f32_16x16x32_bf16 v[104:107], v[162:165], v[188:191], v[104:107]
	v_mfma_f32_16x16x32_bf16 v[100:103], v[172:175], v[188:191], v[100:103]
	v_mfma_f32_16x16x32_bf16 v[88:91], v[162:165], v[208:211], v[88:91]
	v_mfma_f32_16x16x32_bf16 v[84:87], v[172:175], v[208:211], v[84:87]
	v_mfma_f32_16x16x32_bf16 v[72:75], v[162:165], v[216:219], v[72:75]
	v_mfma_f32_16x16x32_bf16 v[68:71], v[172:175], v[216:219], v[68:71]
	v_mfma_f32_16x16x32_bf16 v[120:123], v[166:169], v[184:187], v[120:123]
	v_mfma_f32_16x16x32_bf16 v[116:119], v[176:179], v[184:187], v[116:119]
	v_mfma_f32_16x16x32_bf16 v[104:107], v[166:169], v[192:195], v[104:107]
	v_mfma_f32_16x16x32_bf16 v[100:103], v[176:179], v[192:195], v[100:103]
	v_mfma_f32_16x16x32_bf16 v[88:91], v[166:169], v[212:215], v[88:91]
	v_mfma_f32_16x16x32_bf16 v[84:87], v[176:179], v[212:215], v[84:87]
	v_mfma_f32_16x16x32_bf16 v[72:75], v[166:169], v[220:223], v[72:75]
	v_mfma_f32_16x16x32_bf16 v[68:71], v[176:179], v[220:223], v[68:71]
	s_setprio 0
	s_barrier
	s_add_i32 s66, s82, s64
	v_lshl_add_u64 v[196:197], s[78:79], 0, v[134:135]
	s_mov_b32 m0, s66
	ds_read_b128 v[180:183], v170 offset:16384
	ds_read_b128 v[184:187], v170 offset:17408
	ds_read_b128 v[188:191], v170 offset:18432
	ds_read_b128 v[192:195], v170 offset:19456
	ds_read_b128 v[208:211], v170 offset:20480
	ds_read_b128 v[212:215], v170 offset:21504
	ds_read_b128 v[216:219], v170 offset:22528
	ds_read_b128 v[220:223], v170 offset:23552
	global_load_lds_dwordx4 v[196:197], off
	s_add_i32 m0, s66, 0x2000
	s_add_u32 s82, s78, 0x40000
	v_lshl_add_u64 v[224:225], s[78:79], 0, v[138:139]
	s_addc_u32 s83, s79, 0
	s_add_i32 s53, s53, s64
	global_load_lds_dwordx4 v[224:225], off
	v_lshl_add_u64 v[226:227], s[82:83], 0, v[134:135]
	s_mov_b32 m0, s53
	v_lshl_add_u64 v[228:229], s[80:81], 0, v[136:137]
	global_load_lds_dwordx4 v[226:227], off
	v_lshl_add_u64 v[226:227], s[82:83], 0, v[138:139]
	s_add_i32 m0, s53, 0x2000
	s_nop 0
	global_load_lds_dwordx4 v[226:227], off
	v_lshl_add_u64 v[226:227], s[80:81], 0, v[132:133]
	s_mov_b32 m0, s67
	s_nop 0
	global_load_lds_dwordx4 v[226:227], off
	s_mov_b32 m0, s70
	s_nop 0
	global_load_lds_dwordx4 v[228:229], off
	s_waitcnt vmcnt(8)
	s_waitcnt lgkmcnt(0)
	s_barrier
; #define PG8_STAGE(bufoff, gbase, voff) do { _Pragma("unroll") for (int _i = 0; _i < 2; ++_i) \
;         __builtin_amdgcn_global_load_lds((const unsigned*)((const char*)(gbase) + (voff)[_i]), (LAS unsigned*)(lds + (bufoff) + ldsw + _i * 8192), 16, 0, 0); } while (0)
; #define PG8_LDA(dst, b, h) do { _Pragma("unroll") for (int m = 0; m < 4; ++m) _Pragma("unroll") for (int k = 0; k < 2; ++k) dst[m][k] = *(const LAS bf16x8*)(lds + PG8_SA(b, h) + aoff + m * 2048 + k * 1024); } while (0)
; #define PG8_LDB(dst, b, h) do { _Pragma("unroll") for (int n = 0; n < 2; ++n) _Pragma("unroll") for (int k = 0; k < 2; ++k) dst[n][k] = *(const LAS bf16x8*)(lds + PG8_SB(b, h) + boff + n * 2048 + k * 1024); } while (0)
; #define PG8_MMA(ai, bj, At, Bt) do { __builtin_amdgcn_s_setprio(1); _Pragma("unroll") for (int m = 0; m < 4; ++m) _Pragma("unroll") for (int n = 0; n < 2; ++n) _Pragma("unroll") for (int k = 0; k < 2; ++k) \
;         acc[ai][bj][m][n] = __builtin_amdgcn_mfma_f32_16x16x32_bf16(Bt[n][k], At[m][k], acc[ai][bj][m][n], 0, 0, 0); __builtin_amdgcn_s_setprio(0); } while (0)
; template <class Epi, class Sched, bool HALFN = false>
; __device__ __forceinline__ void gemm_phase(LAS unsigned char* lds, const Gemm g, const Sched& S, const Epi& E, int wave_s) {
;     ...
;             PG8_LDB(B0, 0, 0); if (!HALFN) PG8_LDB(B1, 0, 1); PG8_SCHED; PG8_LDA(At, 0, 0); PG8_STAGE(PG8_SA(1, 1), a1 + hstep, voffA);
;             PG8_WAIT_V(8); PG8_WAIT_L(0); PG8_BAR; PG8_MMA(0, 0, At, B0); if (!HALFN) PG8_MMA(0, 1, At, B1); PG8_BAR; PG8_SCHED;
;             PG8_LDA(At, 0, 1); PG8_STAGE(PG8_SB(0, 0), b2, voffB); PG8_STAGE(PG8_SB(0, 1), b2 + bh1, voffB); PG8_STAGE(PG8_SA(0, 0), a2, voffA);
;             PG8_WAIT_V(8); PG8_WAIT_L(0); PG8_BAR; PG8_MMA(1, 0, At, B0); if (!HALFN) PG8_MMA(1, 1, At, B1); PG8_BAR; PG8_SCHED;
;             PG8_LDB(B0, 1, 0); if (!HALFN) PG8_LDB(B1, 1, 1); PG8_SCHED; PG8_LDA(At, 1, 0); PG8_STAGE(PG8_SA(0, 1), a2 + hstep, voffA);
;             PG8_WAIT_V(8); PG8_WAIT_L(0); PG8_BAR; PG8_MMA(0, 0, At, B0); if (!HALFN) PG8_MMA(0, 1, At, B1); PG8_BAR; PG8_SCHED;
;             PG8_LDA(At, 1, 1); PG8_STAGE(PG8_SB(1, 0), b3, voffB); PG8_STAGE(PG8_SB(1, 1), b3 + bh1, voffB); PG8_STAGE(PG8_SA(1, 0), a3, voffA);
;             PG8_WAIT_V(8); PG8_WAIT_L(0); PG8_BAR; PG8_MMA(1, 0, At, B0); if (!HALFN) PG8_MMA(1, 1, At, B1); PG8_BAR; PG8_SCHED;
	s_setprio 1
	s_waitcnt lgkmcnt(0)
	v_mfma_f32_16x16x32_bf16 v[64:67], v[146:149], v[180:183], v[64:67]
	v_mfma_f32_16x16x32_bf16 v[60:63], v[154:157], v[180:183], v[60:63]
	v_mfma_f32_16x16x32_bf16 v[48:51], v[146:149], v[188:191], v[48:51]
	v_mfma_f32_16x16x32_bf16 v[44:47], v[154:157], v[188:191], v[44:47]
	v_mfma_f32_16x16x32_bf16 v[32:35], v[146:149], v[208:211], v[32:35]
	v_mfma_f32_16x16x32_bf16 v[28:31], v[154:157], v[208:211], v[28:31]
	v_mfma_f32_16x16x32_bf16 v[14:17], v[146:149], v[216:219], v[14:17]
	v_mfma_f32_16x16x32_bf16 v[10:13], v[154:157], v[216:219], v[10:13]
	v_mfma_f32_16x16x32_bf16 v[64:67], v[150:153], v[184:187], v[64:67]
	v_mfma_f32_16x16x32_bf16 v[60:63], v[158:161], v[184:187], v[60:63]
	v_mfma_f32_16x16x32_bf16 v[48:51], v[150:153], v[192:195], v[48:51]
	v_mfma_f32_16x16x32_bf16 v[44:47], v[158:161], v[192:195], v[44:47]
	v_mfma_f32_16x16x32_bf16 v[32:35], v[150:153], v[212:215], v[32:35]
	v_mfma_f32_16x16x32_bf16 v[28:31], v[158:161], v[212:215], v[28:31]
	v_mfma_f32_16x16x32_bf16 v[14:17], v[150:153], v[220:223], v[14:17]
	v_mfma_f32_16x16x32_bf16 v[10:13], v[158:161], v[220:223], v[10:13]
	v_mfma_f32_16x16x32_bf16 v[56:59], v[162:165], v[180:183], v[56:59]
	v_mfma_f32_16x16x32_bf16 v[52:55], v[172:175], v[180:183], v[52:55]
	v_mfma_f32_16x16x32_bf16 v[40:43], v[162:165], v[188:191], v[40:43]
	v_mfma_f32_16x16x32_bf16 v[36:39], v[172:175], v[188:191], v[36:39]
	v_mfma_f32_16x16x32_bf16 v[24:27], v[162:165], v[208:211], v[24:27]
	v_mfma_f32_16x16x32_bf16 v[20:23], v[172:175], v[208:211], v[20:23]
	v_mfma_f32_16x16x32_bf16 v[6:9], v[162:165], v[216:219], v[6:9]
	v_mfma_f32_16x16x32_bf16 v[2:5], v[172:175], v[216:219], v[2:5]
	v_mfma_f32_16x16x32_bf16 v[56:59], v[166:169], v[184:187], v[56:59]
	v_mfma_f32_16x16x32_bf16 v[52:55], v[176:179], v[184:187], v[52:55]
	v_mfma_f32_16x16x32_bf16 v[40:43], v[166:169], v[192:195], v[40:43]
	v_mfma_f32_16x16x32_bf16 v[36:39], v[176:179], v[192:195], v[36:39]
	v_mfma_f32_16x16x32_bf16 v[24:27], v[166:169], v[212:215], v[24:27]
	v_mfma_f32_16x16x32_bf16 v[20:23], v[176:179], v[212:215], v[20:23]
	v_mfma_f32_16x16x32_bf16 v[6:9], v[166:169], v[220:223], v[6:9]
	v_mfma_f32_16x16x32_bf16 v[2:5], v[176:179], v[220:223], v[2:5]
	s_setprio 0
	s_barrier
	s_add_i32 s53, 0, 0x18000
	v_add_u32_e32 v18, s53, v1
	s_add_i32 s66, 0, 0x1c000
	ds_read_b128 v[146:149], v18
	ds_read_b128 v[150:153], v18 offset:1024
	ds_read_b128 v[154:157], v18 offset:2048
	ds_read_b128 v[158:161], v18 offset:3072
	v_add_u32_e32 v18, s66, v1
	ds_read_b128 v[162:165], v18
	ds_read_b128 v[166:169], v18 offset:1024
	ds_read_b128 v[172:175], v18 offset:2048
	ds_read_b128 v[176:179], v18 offset:3072
	s_add_u32 s80, s80, 0x40000
	s_addc_u32 s81, s81, 0
	s_mov_b32 m0, s71
	v_lshl_add_u64 v[230:231], s[80:81], 0, v[132:133]
	ds_read_b128 v[180:183], v170 offset:32768
	ds_read_b128 v[184:187], v170 offset:33792
	ds_read_b128 v[188:191], v170 offset:34816
	ds_read_b128 v[192:195], v170 offset:35840
	ds_read_b128 v[208:211], v170 offset:36864
	ds_read_b128 v[212:215], v170 offset:37888
	ds_read_b128 v[216:219], v170 offset:38912
	ds_read_b128 v[220:223], v170 offset:39936
	global_load_lds_dwordx4 v[230:231], off
	v_lshl_add_u64 v[230:231], s[80:81], 0, v[136:137]
	s_mov_b32 m0, s74
	s_nop 0
	global_load_lds_dwordx4 v[230:231], off
	s_waitcnt vmcnt(8)
	s_waitcnt lgkmcnt(0)
	s_barrier
	s_setprio 1
	s_waitcnt lgkmcnt(0)
	v_mfma_f32_16x16x32_bf16 v[128:131], v[146:149], v[180:183], v[128:131]
	v_mfma_f32_16x16x32_bf16 v[124:127], v[154:157], v[180:183], v[124:127]
	v_mfma_f32_16x16x32_bf16 v[112:115], v[146:149], v[188:191], v[112:115]
	v_mfma_f32_16x16x32_bf16 v[108:111], v[154:157], v[188:191], v[108:111]
	v_mfma_f32_16x16x32_bf16 v[96:99], v[146:149], v[208:211], v[96:99]
	v_mfma_f32_16x16x32_bf16 v[92:95], v[154:157], v[208:211], v[92:95]
	v_mfma_f32_16x16x32_bf16 v[80:83], v[146:149], v[216:219], v[80:83]
	v_mfma_f32_16x16x32_bf16 v[76:79], v[154:157], v[216:219], v[76:79]
	v_mfma_f32_16x16x32_bf16 v[128:131], v[150:153], v[184:187], v[128:131]
	v_mfma_f32_16x16x32_bf16 v[124:127], v[158:161], v[184:187], v[124:127]
	v_mfma_f32_16x16x32_bf16 v[112:115], v[150:153], v[192:195], v[112:115]
	v_mfma_f32_16x16x32_bf16 v[108:111], v[158:161], v[192:195], v[108:111]
	v_mfma_f32_16x16x32_bf16 v[96:99], v[150:153], v[212:215], v[96:99]
	v_mfma_f32_16x16x32_bf16 v[92:95], v[158:161], v[212:215], v[92:95]
	v_mfma_f32_16x16x32_bf16 v[80:83], v[150:153], v[220:223], v[80:83]
	v_mfma_f32_16x16x32_bf16 v[76:79], v[158:161], v[220:223], v[76:79]
	v_mfma_f32_16x16x32_bf16 v[120:123], v[162:165], v[180:183], v[120:123]
	v_mfma_f32_16x16x32_bf16 v[116:119], v[172:175], v[180:183], v[116:119]
	v_mfma_f32_16x16x32_bf16 v[104:107], v[162:165], v[188:191], v[104:107]
	v_mfma_f32_16x16x32_bf16 v[100:103], v[172:175], v[188:191], v[100:103]
	v_mfma_f32_16x16x32_bf16 v[88:91], v[162:165], v[208:211], v[88:91]
	v_mfma_f32_16x16x32_bf16 v[84:87], v[172:175], v[208:211], v[84:87]
	v_mfma_f32_16x16x32_bf16 v[72:75], v[162:165], v[216:219], v[72:75]
	v_mfma_f32_16x16x32_bf16 v[68:71], v[172:175], v[216:219], v[68:71]
	v_mfma_f32_16x16x32_bf16 v[120:123], v[166:169], v[184:187], v[120:123]
	v_mfma_f32_16x16x32_bf16 v[116:119], v[176:179], v[184:187], v[116:119]
	v_mfma_f32_16x16x32_bf16 v[104:107], v[166:169], v[192:195], v[104:107]
	v_mfma_f32_16x16x32_bf16 v[100:103], v[176:179], v[192:195], v[100:103]
	v_mfma_f32_16x16x32_bf16 v[88:91], v[166:169], v[212:215], v[88:91]
	v_mfma_f32_16x16x32_bf16 v[84:87], v[176:179], v[212:215], v[84:87]
	v_mfma_f32_16x16x32_bf16 v[72:75], v[166:169], v[220:223], v[72:75]
	v_mfma_f32_16x16x32_bf16 v[68:71], v[176:179], v[220:223], v[68:71]
	s_setprio 0
	s_barrier
; #define PG8_STAGE(bufoff, gbase, voff) do { _Pragma("unroll") for (int _i = 0; _i < 2; ++_i) \
;         __builtin_amdgcn_global_load_lds((const unsigned*)((const char*)(gbase) + (voff)[_i]), (LAS unsigned*)(lds + (bufoff) + ldsw + _i * 8192), 16, 0, 0); } while (0)
; #define PG8_LDA(dst, b, h) do { _Pragma("unroll") for (int m = 0; m < 4; ++m) _Pragma("unroll") for (int k = 0; k < 2; ++k) dst[m][k] = *(const LAS bf16x8*)(lds + PG8_SA(b, h) + aoff + m * 2048 + k * 1024); } while (0)
; #define PG8_LDB(dst, b, h) do { _Pragma("unroll") for (int n = 0; n < 2; ++n) _Pragma("unroll") for (int k = 0; k < 2; ++k) dst[n][k] = *(const LAS bf16x8*)(lds + PG8_SB(b, h) + boff + n * 2048 + k * 1024); } while (0)
; template <class Epi, class Sched, bool HALFN = false>
; __device__ __forceinline__ void gemm_phase(LAS unsigned char* lds, const Gemm g, const Sched& S, const Epi& E, int wave_s) {
;     ...
;         for (int t = 0; t < nt; t += 2) {
;             const bool last = (t == nt - 2);
;             const char* a1 = cA + (size_t)(t + 1) * kstep;
;             const char* a2 = last ? nA : cA + (size_t)(t + 2) * kstep; const char* b2 = last ? nB : cB + (size_t)(t + 2) * kstep;
;             const char* a3 = a2 + kstep; const char* b3 = b2 + kstep;
;             PG8_LDB(B0, 0, 0); if (!HALFN) PG8_LDB(B1, 0, 1); PG8_SCHED; PG8_LDA(At, 0, 0); PG8_STAGE(PG8_SA(1, 1), a1 + hstep, voffA);
;             PG8_WAIT_V(8); PG8_WAIT_L(0); PG8_BAR; PG8_MMA(0, 0, At, B0); if (!HALFN) PG8_MMA(0, 1, At, B1); PG8_BAR; PG8_SCHED;
;             PG8_LDA(At, 0, 1); PG8_STAGE(PG8_SB(0, 0), b2, voffB); PG8_STAGE(PG8_SB(0, 1), b2 + bh1, voffB); PG8_STAGE(PG8_SA(0, 0), a2, voffA);
;             PG8_WAIT_V(8); PG8_WAIT_L(0); PG8_BAR; PG8_MMA(1, 0, At, B0); if (!HALFN) PG8_MMA(1, 1, At, B1); PG8_BAR; PG8_SCHED;
;             PG8_LDB(B0, 1, 0); if (!HALFN) PG8_LDB(B1, 1, 1); PG8_SCHED; PG8_LDA(At, 1, 0); PG8_STAGE(PG8_SA(0, 1), a2 + hstep, voffA);
;             PG8_WAIT_V(8); PG8_WAIT_L(0); PG8_BAR; PG8_MMA(0, 0, At, B0); if (!HALFN) PG8_MMA(0, 1, At, B1); PG8_BAR; PG8_SCHED;
;             PG8_LDA(At, 1, 1); PG8_STAGE(PG8_SB(1, 0), b3, voffB); PG8_STAGE(PG8_SB(1, 1), b3 + bh1, voffB); PG8_STAGE(PG8_SA(1, 0), a3, voffA);
;             PG8_WAIT_V(8); PG8_WAIT_L(0); PG8_BAR; PG8_MMA(1, 0, At, B0); if (!HALFN) PG8_MMA(1, 1, At, B1); PG8_BAR; PG8_SCHED;
;         }
;         if (wr == 0) PG8_BAR;
	s_add_i32 s53, s53, s64
	v_lshl_add_u64 v[196:197], v[196:197], 0, s[50:51]
	s_mov_b32 m0, s53
	ds_read_b128 v[180:183], v170 offset:49152
	ds_read_b128 v[184:187], v170 offset:50176
	ds_read_b128 v[188:191], v170 offset:51200
	ds_read_b128 v[192:195], v170 offset:52224
	ds_read_b128 v[208:211], v170 offset:53248
	ds_read_b128 v[212:215], v170 offset:54272
	ds_read_b128 v[216:219], v170 offset:55296
	ds_read_b128 v[220:223], v170 offset:56320
	global_load_lds_dwordx4 v[196:197], off
	s_add_i32 m0, s53, 0x2000
	s_add_u32 s78, s78, 0x40080
	v_lshl_add_u64 v[196:197], v[224:225], 0, s[50:51]
	s_addc_u32 s79, s79, 0
	s_add_i32 s53, s66, s64
	global_load_lds_dwordx4 v[196:197], off
	v_lshl_add_u64 v[196:197], s[78:79], 0, v[134:135]
	s_mov_b32 m0, s53
	s_nop 0
	global_load_lds_dwordx4 v[196:197], off
	v_lshl_add_u64 v[196:197], s[78:79], 0, v[138:139]
	s_add_i32 m0, s53, 0x2000
	s_nop 0
	global_load_lds_dwordx4 v[196:197], off
	v_lshl_add_u64 v[196:197], v[226:227], 0, s[50:51]
	s_mov_b32 m0, s75
	s_nop 0
	global_load_lds_dwordx4 v[196:197], off
	v_lshl_add_u64 v[196:197], v[228:229], 0, s[50:51]
	s_mov_b32 m0, s88
	s_nop 0
	global_load_lds_dwordx4 v[196:197], off
	s_waitcnt vmcnt(8)
	s_waitcnt lgkmcnt(0)
	s_barrier
	s_setprio 1
	s_waitcnt lgkmcnt(0)
	v_mfma_f32_16x16x32_bf16 v[64:67], v[146:149], v[180:183], v[64:67]
	v_mfma_f32_16x16x32_bf16 v[60:63], v[154:157], v[180:183], v[60:63]
	v_mfma_f32_16x16x32_bf16 v[48:51], v[146:149], v[188:191], v[48:51]
	v_mfma_f32_16x16x32_bf16 v[44:47], v[154:157], v[188:191], v[44:47]
	v_mfma_f32_16x16x32_bf16 v[32:35], v[146:149], v[208:211], v[32:35]
	v_mfma_f32_16x16x32_bf16 v[28:31], v[154:157], v[208:211], v[28:31]
	v_mfma_f32_16x16x32_bf16 v[14:17], v[146:149], v[216:219], v[14:17]
	v_mfma_f32_16x16x32_bf16 v[10:13], v[154:157], v[216:219], v[10:13]
	v_mfma_f32_16x16x32_bf16 v[64:67], v[150:153], v[184:187], v[64:67]
	v_mfma_f32_16x16x32_bf16 v[60:63], v[158:161], v[184:187], v[60:63]
	v_mfma_f32_16x16x32_bf16 v[48:51], v[150:153], v[192:195], v[48:51]
	v_mfma_f32_16x16x32_bf16 v[44:47], v[158:161], v[192:195], v[44:47]
	v_mfma_f32_16x16x32_bf16 v[32:35], v[150:153], v[212:215], v[32:35]
	v_mfma_f32_16x16x32_bf16 v[28:31], v[158:161], v[212:215], v[28:31]
	v_mfma_f32_16x16x32_bf16 v[14:17], v[150:153], v[220:223], v[14:17]
	v_mfma_f32_16x16x32_bf16 v[10:13], v[158:161], v[220:223], v[10:13]
	v_mfma_f32_16x16x32_bf16 v[56:59], v[162:165], v[180:183], v[56:59]
	v_mfma_f32_16x16x32_bf16 v[52:55], v[172:175], v[180:183], v[52:55]
	v_mfma_f32_16x16x32_bf16 v[40:43], v[162:165], v[188:191], v[40:43]
	v_mfma_f32_16x16x32_bf16 v[36:39], v[172:175], v[188:191], v[36:39]
	v_mfma_f32_16x16x32_bf16 v[24:27], v[162:165], v[208:211], v[24:27]
	v_mfma_f32_16x16x32_bf16 v[20:23], v[172:175], v[208:211], v[20:23]
	v_mfma_f32_16x16x32_bf16 v[6:9], v[162:165], v[216:219], v[6:9]
	v_mfma_f32_16x16x32_bf16 v[2:5], v[172:175], v[216:219], v[2:5]
	v_mfma_f32_16x16x32_bf16 v[56:59], v[166:169], v[184:187], v[56:59]
	v_mfma_f32_16x16x32_bf16 v[52:55], v[176:179], v[184:187], v[52:55]
	v_mfma_f32_16x16x32_bf16 v[40:43], v[166:169], v[192:195], v[40:43]
	v_mfma_f32_16x16x32_bf16 v[36:39], v[176:179], v[192:195], v[36:39]
	v_mfma_f32_16x16x32_bf16 v[24:27], v[166:169], v[212:215], v[24:27]
	v_mfma_f32_16x16x32_bf16 v[20:23], v[176:179], v[212:215], v[20:23]
	v_mfma_f32_16x16x32_bf16 v[6:9], v[166:169], v[220:223], v[6:9]
	v_mfma_f32_16x16x32_bf16 v[2:5], v[176:179], v[220:223], v[2:5]
	s_setprio 0
	s_barrier
	s_add_i32 s52, s52, 2
	s_add_u32 s8, s8, 0x100
	s_addc_u32 s9, s9, 0
	s_add_u32 s47, s47, 0x100
	s_addc_u32 s48, s48, 0
	s_cmp_gt_u32 s52, 13
	s_cbranch_scc0 .LBB0_269
	s_and_b64 vcc, exec, s[26:27]
	s_cbranch_vccz .LBB0_272
	s_barrier
